# intra-workgroup stagger: waves 4-7 enter the Toeplitz streams one s_sleep 2 (half a diagonal) after their SIMD partners
# speedup vs baseline: 1.0059x; 1.0059x over previous
.LBB0_456:
	s_or_b64 exec, exec, s[48:49]
	s_waitcnt vmcnt(1)
	v_lshlrev_b32_e32 v6, 16, v10
	v_and_b32_e32 v10, 0xffff0000, v10
	v_mov_b32_e32 v22, v10
	v_and_b32_e32 v47, 16, v12
	v_and_b32_e32 v46, 0xffff0000, v11
	v_lshlrev_b32_e32 v11, 16, v11
	s_waitcnt vmcnt(1)
	v_lshlrev_b32_e32 v23, 16, v23
	v_pk_mul_f32 v[22:23], v[30:31], v[22:23]
	v_mov_b32_e32 v24, v31
	v_mov_b32_e32 v25, v31
	v_mov_b32_e32 v32, v30
	v_mov_b32_e32 v33, v30
	s_waitcnt vmcnt(0)
	v_lshlrev_b32_e32 v7, 16, v7
	v_pk_fma_f32 v[22:23], v[30:31], v[6:7], v[22:23] op_sel:[0,0,1] op_sel_hi:[1,0,0]
	v_pk_mov_b32 v[30:31], v[10:11], v[46:47] op_sel:[1,0]
	v_mov_b32_e32 v29, v28
	v_and_b32_e32 v39, 0xffff0000, v13
	v_and_b32_e32 v41, 16, v13
	v_and_b32_e32 v40, 0xffff0000, v12
	v_lshlrev_b32_e32 v45, 16, v13
	v_lshlrev_b32_e32 v13, 16, v12
	v_mov_b32_e32 v12, v46
	v_pk_mul_f32 v[30:31], v[32:33], v[30:31]
	v_pk_fma_f32 v[22:23], v[28:29], v[10:11], v[22:23]
	v_pk_fma_f32 v[10:11], v[24:25], v[10:11], v[30:31]
	v_pk_mov_b32 v[30:31], v[12:13], v[40:41] op_sel:[1,0]
	v_mov_b32_e32 v38, v45
	v_pk_mul_f32 v[30:31], v[32:33], v[30:31]
	v_mov_b32_e32 v44, v40
	v_pk_fma_f32 v[10:11], v[28:29], v[12:13], v[10:11]
	v_pk_fma_f32 v[12:13], v[24:25], v[12:13], v[30:31]
	v_pk_mul_f32 v[30:31], v[32:33], v[38:39]
	v_mov_b32_e32 v8, v39
	v_pk_fma_f32 v[24:25], v[24:25], v[44:45], v[30:31]
	s_waitcnt vmcnt(0)
	v_lshlrev_b32_e32 v31, 16, v5
	v_mov_b32_e32 v36, v18
	v_mov_b32_e32 v37, v18
	v_pk_fma_f32 v[12:13], v[28:29], v[44:45], v[12:13]
	s_waitcnt vmcnt(1)
	v_lshlrev_b32_e32 v9, 16, v9
	v_pk_fma_f32 v[8:9], v[28:29], v[8:9], v[24:25]
	v_and_b32_e32 v25, 0xffff0000, v5
	v_and_b32_e32 v28, 0xffff0000, v4
	v_mov_b32_e32 v24, v31
	v_mov_b32_e32 v34, v19
	v_mov_b32_e32 v35, v19
	v_mov_b32_e32 v30, v28
	v_pk_mul_f32 v[32:33], v[36:37], v[24:25]
	v_mov_b32_e32 v17, v16
	v_pk_fma_f32 v[32:33], v[34:35], v[30:31], v[32:33]
	v_mov_b32_e32 v20, v25
	s_waitcnt vmcnt(0)
	v_lshlrev_b32_e32 v21, 16, v21
	v_pk_fma_f32 v[20:21], v[16:17], v[20:21], v[32:33]
	v_and_b32_e32 v32, 0xffff0000, v2
	v_mov_b32_e32 v27, v26
	v_and_b32_e32 v25, 16, v4
	v_and_b32_e32 v24, 0xffff0000, v3
	v_lshlrev_b32_e32 v33, 16, v3
	v_mov_b32_e32 v6, v32
	v_pk_add_f32 v[22:23], v[26:27], v[22:23]
	v_pk_add_f32 v[10:11], v[26:27], v[10:11]
	v_pk_add_f32 v[12:13], v[26:27], v[12:13]
	v_pk_add_f32 v[8:9], v[26:27], v[8:9]
	v_lshlrev_b32_e32 v26, 16, v2
	v_pk_mul_f32 v[2:3], v[18:19], v[6:7]
	v_pk_mov_b32 v[6:7], v[32:33], v[24:25] op_sel:[1,0]
	v_and_b32_e32 v29, 16, v5
	v_pk_mul_f32 v[6:7], v[36:37], v[6:7]
	v_lshlrev_b32_e32 v5, 16, v4
	v_mov_b32_e32 v4, v24
	v_pk_fma_f32 v[2:3], v[18:19], v[26:27], v[2:3] op_sel:[0,0,1] op_sel_hi:[1,0,0]
	v_pk_fma_f32 v[6:7], v[34:35], v[32:33], v[6:7]
	v_mov_b32_e32 v15, v14
	v_pk_fma_f32 v[2:3], v[16:17], v[32:33], v[2:3]
	v_pk_fma_f32 v[6:7], v[16:17], v[4:5], v[6:7]
	v_pk_add_f32 v[2:3], v[14:15], v[2:3]
	v_pk_add_f32 v[6:7], v[14:15], v[6:7]
	v_pk_mul_f32 v[2:3], v[22:23], v[2:3]
	v_pk_mul_f32 v[6:7], v[10:11], v[6:7]
	v_cvt_pk_bf16_f32 v2, v2, v3
	v_cvt_pk_bf16_f32 v3, v6, v7
	v_pk_mov_b32 v[6:7], v[4:5], v[28:29] op_sel:[1,0]
	v_pk_add_f32 v[20:21], v[14:15], v[20:21]
	v_pk_mul_f32 v[6:7], v[36:37], v[6:7]
	s_mov_b64 s[48:49], -1
	v_pk_fma_f32 v[4:5], v[34:35], v[4:5], v[6:7]
	v_pk_mul_f32 v[6:7], v[8:9], v[20:21]
	v_pk_fma_f32 v[4:5], v[16:17], v[30:31], v[4:5]
	s_nop 0
	v_pk_add_f32 v[4:5], v[14:15], v[4:5]
	s_nop 0
	v_pk_mul_f32 v[4:5], v[12:13], v[4:5]
	s_nop 0
	v_cvt_pk_bf16_f32 v4, v4, v5
	v_cvt_pk_bf16_f32 v5, v6, v7
	v_add_u32_e32 v6, s44, v43
	s_and_b64 s[44:45], s[30:31], exec
	v_add_u32_e32 v183, v6, v42
	s_cselect_b32 s44, 10, 14
	ds_write_b128 v183, v[2:5]
	v_lshlrev_b32_e32 v2, s44, v163
	v_add_u32_e32 v117, 0, v2
	v_mov_b32_e32 v2, s47
	v_mad_u32_u24 v182, s85, v163, v2
	v_sub_u32_e32 v2, s46, v111
	v_add_u32_e32 v184, v2, v120
	v_lshrrev_b32_e32 v2, s93, v164
	v_mul_u32_u24_e32 v2, s91, v2
	v_and_b32_e32 v3, s92, v111
	v_add3_u32 v180, v2, s90, v3
	v_lshlrev_b32_e32 v2, 1, v184
	v_add_u32_e32 v3, 0x7f, v180
	s_andn2_b64 vcc, exec, s[42:43]
	v_and_b32_e32 v185, 2, v2
	v_lshrrev_b32_e32 v187, 2, v3
	v_lshlrev_b32_e32 v186, 6, v3
	s_waitcnt lgkmcnt(0)
	s_barrier
	s_cbranch_vccnz .LBB0_472
	v_cmp_gt_u32_e32 vcc, 0x100, v1
	s_cbranch_vccnz .Ltoep_nostag_smp
	s_sleep 2
.Ltoep_nostag_smp:
	v_mov_b32_e32 v2, 0
	v_mov_b32_e32 v3, v2
	v_mov_b32_e32 v4, v2
	v_mov_b32_e32 v5, v2
	v_mov_b32_e32 v6, v2
	v_mov_b32_e32 v7, v2
	v_mov_b32_e32 v8, v2
	v_mov_b32_e32 v9, v2
	v_mov_b32_e32 v10, v2
	v_mov_b32_e32 v11, v2
	v_mov_b32_e32 v12, v2
	v_mov_b32_e32 v13, v2
	v_mov_b32_e32 v14, v2
	v_mov_b32_e32 v15, v2
	v_mov_b32_e32 v16, v2
	v_mov_b32_e32 v17, v2
	v_mov_b32_e32 v18, v2
	v_mov_b32_e32 v19, v2
	v_mov_b32_e32 v20, v2
	v_mov_b32_e32 v21, v2
	v_mov_b32_e32 v22, v2
	v_mov_b32_e32 v23, v2
	v_mov_b32_e32 v24, v2
	v_mov_b32_e32 v25, v2
	v_mov_b32_e32 v26, v2
	v_mov_b32_e32 v27, v2
	v_mov_b32_e32 v28, v2
	v_mov_b32_e32 v29, v2
	v_mov_b32_e32 v30, v2
	v_mov_b32_e32 v31, v2
	v_mov_b32_e32 v32, v2
	v_mov_b32_e32 v33, v2
	v_mov_b32_e32 v34, v2
	v_mov_b32_e32 v35, v2
	v_mov_b32_e32 v36, v2
	v_mov_b32_e32 v37, v2
	v_mov_b32_e32 v38, v2
	v_mov_b32_e32 v39, v2
	v_mov_b32_e32 v40, v2
	v_mov_b32_e32 v41, v2
	v_mov_b32_e32 v42, v2
	v_mov_b32_e32 v43, v2
	v_mov_b32_e32 v44, v2
	v_mov_b32_e32 v45, v2
	v_mov_b32_e32 v46, v2
	v_mov_b32_e32 v47, v2
	v_mov_b32_e32 v48, v2
	v_mov_b32_e32 v49, v2
	v_mov_b32_e32 v50, v2
	v_mov_b32_e32 v51, v2
	v_mov_b32_e32 v52, v2
	v_mov_b32_e32 v53, v2
	v_mov_b32_e32 v54, v2
	v_mov_b32_e32 v55, v2
	v_mov_b32_e32 v56, v2
	v_mov_b32_e32 v57, v2
	v_mov_b32_e32 v58, v2
	v_mov_b32_e32 v59, v2
	v_mov_b32_e32 v60, v2
	v_mov_b32_e32 v61, v2
	v_mov_b32_e32 v62, v2
	v_mov_b32_e32 v63, v2
	v_mov_b32_e32 v64, v2
	v_mov_b32_e32 v65, v2
	v_lshlrev_b32_e32 v206, 1, v184
	v_and_b32_e32 v206, -4, v206
	v_add_u32_e32 v206, 0x1fc0, v206
	v_add_u32_e32 v206, v117, v206
	v_add_u32_e32 v209, 0x7f, v180
	v_lshrrev_b32_e32 v210, 2, v209
	v_lshl_add_u32 v189, v209, 6, v182
	v_bitop3_b32 v211, v210, v113, 3 bitop3:0x6c
	v_bitop3_b32 v188, v210, v155, 3 bitop3:0x6c
	v_lshl_add_u32 v207, v211, 4, v189
	v_lshl_add_u32 v208, v188, 4, v189
	ds_read2_b32 v[194:195], v206 offset1:1
	ds_read2_b32 v[196:197], v206 offset0:2 offset1:3
	ds_read_b32 v198, v206 offset:16
	ds_read2_b32 v[200:201], v206 offset0:8 offset1:9
	ds_read2_b32 v[202:203], v206 offset0:10 offset1:11
	ds_read_b32 v204, v206 offset:48
	ds_read_b128 v[66:69], v207
	ds_read_b128 v[70:73], v208
	v_add_u32_e32 v209, -1, v209
	v_lshrrev_b32_e32 v210, 2, v209
	v_lshl_add_u32 v189, v209, 6, v182
	v_bitop3_b32 v211, v210, v113, 3 bitop3:0x6c
	v_bitop3_b32 v188, v210, v155, 3 bitop3:0x6c
	v_lshl_add_u32 v207, v211, 4, v189
	v_lshl_add_u32 v208, v188, 4, v189
	s_movk_i32 s42, 0xff81

.LBB0_472:
	s_and_b64 vcc, exec, s[48:49]
	s_cbranch_vccz .LBB0_475
	v_cmp_gt_u32_e32 vcc, 0x100, v1
	s_cbranch_vccnz .Ltoep_nostag_pr
	s_sleep 2
.Ltoep_nostag_pr:
	v_mov_b32_e32 v2, 0
	v_mov_b32_e32 v3, v2
	v_mov_b32_e32 v4, v2
	v_mov_b32_e32 v5, v2
	v_mov_b32_e32 v6, v2
	v_mov_b32_e32 v7, v2
	v_mov_b32_e32 v8, v2
	v_mov_b32_e32 v9, v2
	v_mov_b32_e32 v10, v2
	v_mov_b32_e32 v11, v2
	v_mov_b32_e32 v12, v2
	v_mov_b32_e32 v13, v2
	v_mov_b32_e32 v14, v2
	v_mov_b32_e32 v15, v2
	v_mov_b32_e32 v16, v2
	v_mov_b32_e32 v17, v2
	v_mov_b32_e32 v18, v2
	v_mov_b32_e32 v19, v2
	v_mov_b32_e32 v20, v2
	v_mov_b32_e32 v21, v2
	v_mov_b32_e32 v22, v2
	v_mov_b32_e32 v23, v2
	v_mov_b32_e32 v24, v2
	v_mov_b32_e32 v25, v2
	v_mov_b32_e32 v26, v2
	v_mov_b32_e32 v27, v2
	v_mov_b32_e32 v28, v2
	v_mov_b32_e32 v29, v2
	v_mov_b32_e32 v30, v2
	v_mov_b32_e32 v31, v2
	v_mov_b32_e32 v32, v2
	v_mov_b32_e32 v33, v2
	v_mov_b32_e32 v34, v2
	v_mov_b32_e32 v35, v2
	v_mov_b32_e32 v36, v2
	v_mov_b32_e32 v37, v2
	v_mov_b32_e32 v38, v2
	v_mov_b32_e32 v39, v2
	v_mov_b32_e32 v40, v2
	v_mov_b32_e32 v41, v2
	v_mov_b32_e32 v42, v2
	v_mov_b32_e32 v43, v2
	v_mov_b32_e32 v44, v2
	v_mov_b32_e32 v45, v2
	v_mov_b32_e32 v46, v2
	v_mov_b32_e32 v47, v2
	v_mov_b32_e32 v48, v2
	v_mov_b32_e32 v49, v2
	v_mov_b32_e32 v50, v2
	v_mov_b32_e32 v51, v2
	v_mov_b32_e32 v52, v2
	v_mov_b32_e32 v53, v2
	v_mov_b32_e32 v54, v2
	v_mov_b32_e32 v55, v2
	v_mov_b32_e32 v56, v2
	v_mov_b32_e32 v57, v2
	v_mov_b32_e32 v58, v2
	v_mov_b32_e32 v59, v2
	v_mov_b32_e32 v60, v2
	v_mov_b32_e32 v61, v2
	v_mov_b32_e32 v62, v2
	v_mov_b32_e32 v63, v2
	v_mov_b32_e32 v64, v2
	v_mov_b32_e32 v65, v2
	v_lshlrev_b32_e32 v206, 1, v184
	v_and_b32_e32 v206, -4, v206
	v_add_u32_e32 v206, 0x1c0, v206
	v_add_u32_e32 v206, v117, v206
	v_add_u32_e32 v209, 7, v180
	ds_read2_b32 v[194:195], v206 offset1:1
	ds_read2_b32 v[196:197], v206 offset0:2 offset1:3
	ds_read_b32 v198, v206 offset:16
	ds_read2_b32 v[200:201], v206 offset0:8 offset1:9
	ds_read2_b32 v[202:203], v206 offset0:10 offset1:11
	ds_read_b32 v204, v206 offset:48
	v_lshrrev_b32_e32 v210, 2, v209
	v_lshl_add_u32 v189, v209, 6, v182
	v_bitop3_b32 v211, v210, v113, 3 bitop3:0x6c
	v_bitop3_b32 v188, v210, v155, 3 bitop3:0x6c
	v_lshl_add_u32 v199, v211, 4, v189
	v_lshl_add_u32 v205, v188, 4, v189
	ds_read_b128 v[66:69], v199
	ds_read_b128 v[70:73], v205
	v_add_u32_e32 v207, 60, v209
	v_lshrrev_b32_e32 v210, 2, v207
	v_lshl_add_u32 v189, v207, 6, v182
	v_bitop3_b32 v211, v210, v113, 3 bitop3:0x6c
	v_bitop3_b32 v188, v210, v155, 3 bitop3:0x6c
	v_lshl_add_u32 v199, v211, 4, v189
	v_lshl_add_u32 v205, v188, 4, v189
	ds_read_b128 v[74:77], v199
	ds_read_b128 v[78:81], v205
	v_add_u32_e32 v207, 120, v209
	v_lshrrev_b32_e32 v210, 2, v207
	v_lshl_add_u32 v189, v207, 6, v182
	v_bitop3_b32 v211, v210, v113, 3 bitop3:0x6c
	v_bitop3_b32 v188, v210, v155, 3 bitop3:0x6c
	v_lshl_add_u32 v199, v211, 4, v189
	v_lshl_add_u32 v205, v188, 4, v189
	ds_read_b128 v[82:85], v199
	ds_read_b128 v[86:89], v205
	v_add_u32_e32 v207, 180, v209
	v_lshrrev_b32_e32 v210, 2, v207
	v_lshl_add_u32 v189, v207, 6, v182
	v_bitop3_b32 v211, v210, v113, 3 bitop3:0x6c
	v_bitop3_b32 v188, v210, v155, 3 bitop3:0x6c
	v_lshl_add_u32 v199, v211, 4, v189
	v_lshl_add_u32 v205, v188, 4, v189
	ds_read_b128 v[90:93], v199
	ds_read_b128 v[94:97], v205
	v_add_u32_e32 v209, -1, v209
	s_mov_b32 s42, -7
